# combine loop: norm-weight loads hoisted out of the loop, next iteration's OF/OB/Z tile loads prefetched into a second register set
# baseline (speedup 1.0000x reference)
.LBB0_173:
	v_readlane_b32 s1, v254, 56
	s_andn2_b64 vcc, exec, s[36:37]
	s_mov_b32 s36, s1
	v_readlane_b32 s1, v254, 57
	s_mov_b32 s44, s1
	s_cbranch_vccnz .LBB0_183
	s_waitcnt vmcnt(0) lgkmcnt(0)
	v_mov_b32_e32 v6, v168
	v_mov_b32_e32 v0, v168
	v_readlane_b32 s0, v254, 7
	v_ashrrev_i32_e32 v0, 6, v0
	s_nop 0
	v_add_u32_e32 v0, s0, v0
	v_readlane_b32 s0, v254, 46
	v_readlane_b32 s1, v254, 47
	s_movk_i32 s1, 0x3000
	s_nop 0
	v_cmp_gt_i32_e32 vcc, s1, v0
	s_and_saveexec_b64 s[36:37], vcc
	s_cbranch_execz .LBB0_177
	v_cmp_lt_i32_e32 vcc, v185, v182
	v_lshlrev_b32_e32 v1, 3, v6
	v_readlane_b32 s2, v254, 63
	v_cndmask_b32_e32 v3, v179, v185, vcc
	v_cmp_lt_i32_e32 vcc, v186, v182
	v_readlane_b32 s40, v250, 33
	v_readlane_b32 s41, v250, 34
	v_cndmask_b32_e32 v4, v179, v186, vcc
	v_cmp_lt_i32_e32 vcc, v187, v182
	v_lshlrev_b32_e32 v8, 2, v4
	v_lshlrev_b32_e32 v3, 2, v3
	v_cndmask_b32_e32 v4, v179, v187, vcc
	v_lshlrev_b32_e32 v9, 2, v4
	v_and_or_b32 v4, v1, 56, s2
	v_ashrrev_i32_e32 v1, 31, v0
	v_lshlrev_b64 v[10:11], 10, v[0:1]
	v_and_b32_e32 v1, 63, v6
	v_readlane_b32 s2, v254, 13
	v_ashrrev_i32_e32 v5, 31, v4
	v_lshl_or_b32 v10, v1, 4, v10
	v_readlane_b32 s3, v254, 14
	v_lshl_add_u64 v[4:5], v[4:5], 2, s[40:41]
	s_mov_b64 s[38:39], 0
	v_lshl_add_u64 v[6:7], s[2:3], 0, v[10:11]
	v_readlane_b32 s42, v250, 35
	v_readlane_b32 s43, v250, 36
	v_readlane_b32 s44, v250, 37
	v_readlane_b32 s45, v250, 38
	v_readlane_b32 s46, v250, 39
	v_readlane_b32 s47, v250, 40
	v_readlane_b32 s48, v250, 41
	v_readlane_b32 s49, v250, 42
	v_readlane_b32 s50, v250, 43
	v_readlane_b32 s51, v250, 44
	v_readlane_b32 s52, v250, 45
	v_readlane_b32 s53, v250, 46
	v_readlane_b32 s54, v250, 47
	v_readlane_b32 s55, v250, 48
	global_load_dwordx4 v[46:49], v[4:5], off offset:16
	global_load_dwordx4 v[50:53], v[4:5], off
	v_add_co_u32_e32 v66, vcc, 0xf9720000, v6
	s_nop 1
	v_addc_co_u32_e32 v67, vcc, -1, v7, vcc
	v_add_co_u32_e32 v68, vcc, 0x3b80000, v6
	s_nop 1
	v_addc_co_u32_e32 v69, vcc, 0, v7, vcc
	global_load_dwordx4 v[54:57], v[66:67], off
	global_load_dwordx4 v[58:61], v[68:69], off
	global_load_dwordx4 v[62:65], v[6:7], off
.LBB0_176:
	s_waitcnt vmcnt(0)
	v_mov_b32_e32 v10, v54
	v_mov_b32_e32 v11, v55
	v_mov_b32_e32 v12, v56
	v_mov_b32_e32 v13, v57
	v_mov_b32_e32 v14, v58
	v_mov_b32_e32 v15, v59
	v_mov_b32_e32 v16, v60
	v_mov_b32_e32 v17, v61
	v_mov_b32_e32 v18, v62
	v_mov_b32_e32 v19, v63
	v_mov_b32_e32 v20, v64
	v_mov_b32_e32 v21, v65
	v_mov_b32_e32 v28, v66
	v_mov_b32_e32 v29, v67
	v_add_u32_e32 v0, s0, v0
	v_cmp_lt_i32_e32 vcc, s35, v0
	s_or_b64 s[38:39], vcc, s[38:39]
	s_mov_b64 s[20:21], exec
	s_andn2_b64 exec, exec, s[38:39]
	s_cbranch_execz .Lmy_cmb_nopf
	v_lshl_add_u64 v[6:7], v[6:7], 0, s[76:77]
	v_add_co_u32_e32 v66, vcc, 0xf9720000, v6
	s_nop 1
	v_addc_co_u32_e32 v67, vcc, -1, v7, vcc
	v_add_co_u32_e32 v68, vcc, 0x3b80000, v6
	s_nop 1
	v_addc_co_u32_e32 v69, vcc, 0, v7, vcc
	global_load_dwordx4 v[54:57], v[66:67], off
	global_load_dwordx4 v[58:61], v[68:69], off
	global_load_dwordx4 v[62:65], v[6:7], off
.Lmy_cmb_nopf:
	s_mov_b64 exec, s[20:21]
	v_lshlrev_b32_e32 v22, 16, v13
	v_and_b32_e32 v23, 0xffff0000, v13
	v_lshlrev_b32_e32 v24, 16, v17
	v_and_b32_e32 v25, 0xffff0000, v17
	v_pk_add_f32 v[32:33], v[22:23], v[24:25]
	v_lshlrev_b32_e32 v22, 16, v12
	v_and_b32_e32 v23, 0xffff0000, v12
	v_lshlrev_b32_e32 v12, 16, v16
	v_and_b32_e32 v13, 0xffff0000, v16
	v_lshlrev_b32_e32 v30, 16, v21
	v_and_b32_e32 v31, 0xffff0000, v21
	v_lshlrev_b32_e32 v16, 16, v20
	v_and_b32_e32 v17, 0xffff0000, v20
	v_pk_add_f32 v[12:13], v[22:23], v[12:13]
	v_mul_f32_e32 v1, 0xbfb8aa3b, v16
	v_exp_f32_e32 v1, v1
	v_lshlrev_b32_e32 v42, 16, v19
	v_and_b32_e32 v43, 0xffff0000, v19
	v_lshlrev_b32_e32 v40, 16, v15
	v_add_f32_e32 v1, 1.0, v1
	v_rcp_f32_e32 v38, v1
	v_mul_f32_e32 v1, 0xbfb8aa3b, v17
	v_exp_f32_e32 v1, v1
	v_and_b32_e32 v41, 0xffff0000, v15
	v_and_b32_e32 v15, 0xffff0000, v18
	v_pk_mul_f32 v[36:37], v[12:13], v[12:13]
	v_add_f32_e32 v1, 1.0, v1
	v_rcp_f32_e32 v39, v1
	v_mul_f32_e32 v1, 0xbfb8aa3b, v42
	v_exp_f32_e32 v1, v1
	v_pk_mul_f32 v[34:35], v[32:33], v[32:33]
	v_pk_mul_f32 v[16:17], v[38:39], v[16:17]
	v_lshlrev_b32_e32 v38, 16, v11
	v_add_f32_e32 v1, 1.0, v1
	v_rcp_f32_e32 v44, v1
	v_mul_f32_e32 v1, 0xbfb8aa3b, v43
	v_exp_f32_e32 v1, v1
	v_and_b32_e32 v39, 0xffff0000, v11
	v_and_b32_e32 v11, 0xffff0000, v14
	v_pk_add_f32 v[38:39], v[38:39], v[40:41]
	v_add_f32_e32 v1, 1.0, v1
	v_rcp_f32_e32 v45, v1
	v_pk_mul_f32 v[40:41], v[38:39], v[38:39]
	v_pk_mul_f32 v[42:43], v[44:45], v[42:43]
	v_lshlrev_b32_e32 v44, 16, v10
	v_and_b32_e32 v45, 0xffff0000, v10
	v_lshlrev_b32_e32 v10, 16, v14
	v_lshlrev_b32_e32 v14, 16, v18
	v_mul_f32_e32 v1, 0xbfb8aa3b, v14
	v_exp_f32_e32 v1, v1
	v_pk_add_f32 v[10:11], v[44:45], v[10:11]
	v_add_f32_e32 v1, 1.0, v1
	v_rcp_f32_e32 v44, v1
	v_mul_f32_e32 v1, 0xbfb8aa3b, v15
	v_exp_f32_e32 v1, v1
	v_pk_mul_f32 v[18:19], v[10:11], v[10:11]
	v_add_f32_e32 v1, 1.0, v1
	v_rcp_f32_e32 v45, v1
	v_add_f32_e32 v1, v18, v19
	v_add_f32_e32 v1, v40, v1
	v_add_f32_e32 v1, v41, v1
	v_add_f32_e32 v1, v36, v1
	v_add_f32_e32 v1, v37, v1
	v_add_f32_e32 v1, v34, v1
	v_add_f32_e32 v1, v35, v1
	ds_bpermute_b32 v18, v3, v1
	v_pk_mul_f32 v[14:15], v[44:45], v[14:15]
	s_waitcnt lgkmcnt(0)
	v_add_f32_e32 v1, v1, v18
	ds_bpermute_b32 v18, v8, v1
	s_waitcnt lgkmcnt(0)
	v_add_f32_e32 v1, v1, v18
	ds_bpermute_b32 v18, v9, v1
	s_waitcnt lgkmcnt(0)
	v_add_f32_e32 v1, v1, v18
	v_fmamk_f32 v1, v1, 0x3c800000, v174
	v_rsq_f32_e32 v18, v1
	v_mul_f32_e32 v1, 0xbfb8aa3b, v30
	v_exp_f32_e32 v1, v1
	v_pk_mul_f32 v[12:13], v[12:13], v[18:19] op_sel_hi:[1,0]
	v_pk_mul_f32 v[12:13], v[46:47], v[12:13]
	v_add_f32_e32 v1, 1.0, v1
	v_pk_mul_f32 v[12:13], v[16:17], v[12:13]
	v_rcp_f32_e32 v16, v1
	v_mul_f32_e32 v1, 0xbfb8aa3b, v31
	v_exp_f32_e32 v1, v1
	v_pk_mul_f32 v[10:11], v[10:11], v[18:19] op_sel_hi:[1,0]
	v_cvt_pk_bf16_f32 v12, v12, v13
	v_pk_mul_f32 v[10:11], v[50:51], v[10:11]
	v_add_f32_e32 v1, 1.0, v1
	v_rcp_f32_e32 v17, v1
	v_pk_mul_f32 v[10:11], v[14:15], v[10:11]
	v_pk_mul_f32 v[14:15], v[38:39], v[18:19] op_sel_hi:[1,0]
	v_pk_mul_f32 v[18:19], v[32:33], v[18:19] op_sel_hi:[1,0]
	v_pk_mul_f32 v[14:15], v[52:53], v[14:15]
	v_pk_mul_f32 v[18:19], v[48:49], v[18:19]
	v_pk_mul_f32 v[16:17], v[16:17], v[30:31]
	v_pk_mul_f32 v[14:15], v[42:43], v[14:15]
	v_pk_mul_f32 v[16:17], v[16:17], v[18:19]
	v_cvt_pk_bf16_f32 v10, v10, v11
	v_cvt_pk_bf16_f32 v11, v14, v15
	v_cvt_pk_bf16_f32 v13, v16, v17
	global_store_dwordx4 v[28:29], v[10:13], off
	s_andn2_b64 exec, exec, s[38:39]
	s_cbranch_execnz .LBB0_176
